# NA+conv phase: waves 4-7 run their conv items before their attention tasks (phase probe: 131.7 -> 125.6 us)
# speedup vs baseline: 1.0074x; 1.0074x over previous
; __device__ __forceinline__ void na_task(const P& p, int task, int lane, float* ldsw  ) {
;     const int fr = lane & 15, g = lane >> 4;
;     const bf16_t* QK = (const bf16_t*)(p.ws + WS_NAQK); const bf16_t* VT = (const bf16_t*)(p.ws + WS_NAVT); bf16_t* Y = (bf16_t*)(p.ws + WS_A);
;     if (task < 2048) {
;         const int h = task & 7, r = (task >> 3) & 31, b = task >> 8;
;         for (int i = lane; i < 465; i += 64) ldsw[i] = p.rpb[h * 465 + i];
;         AttnState st[4];
;         bf16_t* qlds = (bf16_t*)(ldsw + 512) + fr * 72 + g * 8;
;         const size_t qrow0 = (size_t)b * TLAT + r * 64 + fr;
; #pragma unroll
;         for (int j = 0; j < 4; ++j) {
;             st[j].m = -1e30f; st[j].l = 0.f;
; #pragma unroll
;             for (int dt = 0; dt < 4; ++dt) st[j].o[dt] = (f32x4){0.f, 0.f, 0.f, 0.f};
;             const bf16_t* qp = QK + (qrow0 + j * 16) * 1024 + h * 64 + g * 8;
;             *(bf16x8*)(qlds + j * 16 * 72) = *(const bf16x8*)qp; *(bf16x8*)(qlds + j * 16 * 72 + 32) = *(const bf16x8*)(qp + 32);
;         }
;         const int r0 = clampi(r - 4, 0, 24);
;         const bf16_t* vb = VT + ((size_t)b * 512 + h * 64) * TT;
;         const bf16_t* kbase = QK + 512 + h * 64 + g * 8;
;         auto ldk = [&](int i, AttnKn& k) {
;             const bf16_t* k0p = (i < 16) ? kbase + ((size_t)b * TLAT + (r0 + (i >> 1)) * 64 + (i & 1) * 32 + fr) * 1024 : kbase + ((size_t)MLAT + b * TCTX + (i - 16) * 32 + fr) * 1024;
;             k.a00 = *(const bf16x8*)k0p; k.a01 = *(const bf16x8*)(k0p + 32); k.a10 = *(const bf16x8*)(k0p + 16 * 1024); k.a11 = *(const bf16x8*)(k0p + 16 * 1024 + 32);
;         };
;         auto ldv = [&](int i, AttnVn& v) {
;             const int tok0 = (i < 16) ? (r0 + (i >> 1)) * 64 + (i & 1) * 32 : TLAT + (i - 16) * 32;
; #pragma unroll
;             for (int dt = 0; dt < 4; ++dt) { const bf16_t* vp = vb + (size_t)(dt * 16 + fr) * TT + tok0 + 4 * g; v.va[dt][0] = *(const s16x4*)vp; v.va[dt][1] = *(const s16x4*)(vp + 16); }
;         };
;         asm volatile("s_waitcnt lgkmcnt(0)" ::: "memory");
;         AttnKn kc, kn; AttnVn vv; ldk(0, kc);
; #pragma unroll 1
;         for (int i = 0; i < 24; ++i) {
;             ldk(i + 1 < 24 ? i + 1 : i, kn);
;             ldv(i, vv);
;             const int half = i & 1;
;             const float* rp = ldsw + (r0 + (i >> 1) - r + 7) * 31;
; #pragma unroll
.LBB0_378:
	s_or_b64 exec, exec, s[2:3]
	v_mov_b32_e32 v0, v1
	s_waitcnt lgkmcnt(0)
	s_barrier
	v_readfirstlane_b32 s32, v144
	s_lshr_b32 s32, s32, 8
	s_cmp_eq_u32 s32, 0
	s_cbranch_scc1 .Lst_na
	s_branch .LBB0_418
.Lst_na:
	v_readlane_b32 s2, v254, 18
	v_readfirstlane_b32 s49, v144
	s_ashr_i32 s48, s49, 6
	s_add_i32 s84, s2, s48
	s_cmpk_gt_i32 s84, 0xbff
	v_readfirstlane_b32 s2, v0
	s_cbranch_scc1 .LBB0_418
	s_load_dwordx2 s[44:45], s[92:93], s2 offset:0x58
	s_load_dwordx2 s[46:47], s[92:93], s2 offset:0xa8
	s_mul_i32 s2, s48, 0x3000
	v_and_b32_e32 v2, 48, v144
	v_mov_b32_e32 v3, v1
	s_add_i32 s85, s2, 0
	v_and_b32_e32 v114, 15, v144
	s_waitcnt lgkmcnt(0)
	v_lshl_add_u64 v[4:5], s[46:47], 0, v[2:3]
	s_mov_b64 s[6:7], 0x7f00400
	s_add_u32 s2, s46, 0x7f00000
	v_lshl_add_u64 v[116:117], v[4:5], 0, s[6:7]
	v_mul_u32_u24_e32 v4, 0x90, v114
	v_bfe_u32 v6, v144, 4, 2
	s_addc_u32 s3, s47, 0
	v_add3_u32 v143, s85, v4, v2
	v_subrev_co_u32_e32 v4, vcc, 8, v114
	s_add_u32 s86, s46, 0xa300000
	v_min_u32_e32 v4, 48, v4
	v_lshlrev_b32_e32 v124, 2, v6
	s_addc_u32 s87, s47, 0
	v_cndmask_b32_e64 v8, v4, 0, vcc
	v_or_b32_e32 v170, 16, v124
	s_add_u32 s76, s46, 0x5b00000
	v_add_u32_e32 v9, 16, v8
	v_cmp_lt_u32_e64 s[8:9], v124, v8
	v_cmp_ge_u32_e32 vcc, v170, v8
	v_or_b32_e32 v172, 17, v124
	s_addc_u32 s77, s47, 0
	s_and_b64 s[14:15], vcc, s[8:9]
	v_cmp_ge_u32_e32 vcc, v172, v8
	v_cmp_lt_u32_e64 s[16:17], v172, v9
	v_or_b32_e32 v174, 18, v124
	v_and_b32_e32 v7, 63, v144
	v_or_b32_e32 v167, 1, v124
	v_or_b32_e32 v168, 3, v124
	v_or_b32_e32 v169, 2, v124
	v_sub_u32_e32 v10, v170, v114
	s_and_b64 s[16:17], vcc, s[16:17]
	v_cmp_ge_u32_e32 vcc, v174, v8
	v_cmp_lt_u32_e64 s[18:19], v174, v9
	v_or_b32_e32 v176, 19, v124
	v_or_b32_e32 v5, 48, v7
	v_cmp_lt_u32_e64 s[6:7], v167, v8
	v_cmp_lt_u32_e64 s[10:11], v168, v8
	v_cmp_lt_u32_e64 s[12:13], v169, v8
	v_min_u32_e32 v171, 15, v10
	v_sub_u32_e32 v10, v172, v114
	s_and_b64 s[18:19], vcc, s[18:19]
	v_cmp_ge_u32_e32 vcc, v176, v8
	v_sub_u32_e32 v8, v176, v114
	v_min_u32_e32 v173, 15, v10
	v_sub_u32_e32 v10, v174, v114
	v_min_u32_e32 v177, 15, v8
	v_add_u32_e32 v8, -8, v5
	v_min_u32_e32 v175, 15, v10
	v_min_u32_e32 v8, 48, v8
	v_or_b32_e32 v10, 32, v124
	v_cmp_lt_u32_e64 s[22:23], v10, v8
	v_sub_u32_e32 v10, v10, v5
	v_sub_u32_e64 v183, v10, -15 clamp
	v_or_b32_e32 v10, 33, v124
	v_cmp_lt_u32_e64 s[24:25], v10, v8
	v_sub_u32_e32 v10, v10, v5
	v_sub_u32_e64 v207, v10, -15 clamp
	v_or_b32_e32 v10, 34, v124
	v_cmp_lt_u32_e64 s[26:27], v10, v8
	v_sub_u32_e32 v10, v10, v5
	s_bfe_u32 s49, s49, 0x30006
	v_sub_u32_e64 v208, v10, -15 clamp
	v_or_b32_e32 v10, 35, v124
	v_lshl_add_u64 v[2:3], s[2:3], 0, v[2:3]
	s_lshl_b32 s64, s49, 7
	v_cmp_lt_u32_e64 s[20:21], v176, v9
	v_add_u32_e32 v9, 16, v8
	v_cmp_lt_u32_e64 s[28:29], v10, v8
	v_sub_u32_e32 v8, v10, v5
	v_lshl_add_u64 v[126:127], v[2:3], 0, s[64:65]
	v_lshrrev_b32_e32 v2, 1, v144
	v_sub_u32_e64 v209, v8, -15 clamp
	v_or_b32_e32 v8, 49, v124
	v_or_b32_e32 v10, 48, v124
	v_and_b32_e32 v2, 24, v2
	v_mov_b32_e32 v3, v1
	v_lshlrev_b32_e32 v0, 3, v6
	v_sub_u32_e32 v210, v10, v5
	v_cmp_lt_u32_e64 s[30:31], v8, v9
	v_cmp_lt_u32_e64 s[34:35], v10, v9
	v_or_b32_e32 v8, 51, v124
	v_or_b32_e32 v10, 50, v124
	s_mul_i32 s50, s49, 0x1d1
	v_lshl_add_u64 v[132:133], s[46:47], 0, v[2:3]
	v_readlane_b32 s46, v254, 19
	v_mul_u32_u24_e32 v118, 0x1200, v114
	v_or_b32_e32 v4, 0x800, v124
	v_or_b32_e32 v6, 0x810, v124
	v_cmp_lt_u32_e64 s[40:41], v8, v9
	v_cmp_lt_u32_e64 s[42:43], v10, v9
	v_lshl_add_u64 v[8:9], s[76:77], 0, v[0:1]
	s_add_i32 s89, s46, s48
	s_lshl_b32 s46, s48, 6
	v_readlane_b32 s47, v254, 21
	v_add_lshl_u32 v2, s50, v7, 2
	v_mov_b32_e32 v119, v1
	v_mul_u32_u24_e32 v120, 0x1200, v5
	v_mov_b32_e32 v121, v1
	v_or_b32_e32 v125, 0x4000, v114
	v_mov_b32_e32 v115, v1
	v_mul_hi_u32_u24_e32 v123, 0x1200, v114
	v_mov_b32_e32 v122, v118
	v_bitop3_b32 v145, v144, 15, v144 bitop3:0xc
	s_and_b64 s[20:21], vcc, s[20:21]
	v_or_b32_e32 v178, 16, v114
	v_add_u32_e32 v179, 8, v114
	v_add_u32_e32 v180, 24, v114
	v_or_b32_e32 v181, 32, v114
	v_add_u32_e32 v182, 40, v114
	v_sub_u32_e32 v211, v10, v5
	s_lshl_b32 s88, s49, 6
	v_lshl_add_u64 v[128:129], v[116:117], 0, s[64:65]
	v_lshl_add_u64 v[130:131], v[8:9], 0, s[64:65]
	s_add_i32 s90, s47, s46
	v_lshl_add_u32 v212, v7, 2, s85
	v_or_b32_e32 v213, 0xffffffc0, v7
	v_lshl_add_u64 v[134:135], s[44:45], 0, v[2:3]
	v_lshlrev_b32_e32 v136, 1, v0
	v_lshlrev_b32_e32 v146, 1, v4
	v_lshlrev_b32_e32 v148, 1, v6
	s_branch .LBB0_382
	s_nop 0
	s_nop 0
	s_nop 0
	s_nop 0
	s_nop 0
	s_nop 0
	s_nop 0

; #define REP(k) for (int rep_ = 0; rep_ < (((REPMASK) >> (k)) & 1) + 1; ++rep_)
; __device__ __forceinline__ void dn_conv_token4(const P& p, int m0, int lane) {
;     const bf16_t* PRE = (const bf16_t*)(p.ws + WS_DNPRE);
;     int s0, s1;
;     if (m0 < MLAT) { s0 = m0 & ~2047; s1 = s0 + 2048; } else { s0 = MLAT + ((m0 - MLAT) & ~255); s1 = s0 + 256; }
; #pragma unroll 1
;     for (int cgp = 0; cgp < 3; ++cgp) {
;         const int col = cgp * 512 + lane * 8;
;         f32x4 w[5][2];
; #pragma unroll
;         for (int j = 0; j < 5; ++j) { w[j][0] = *(const f32x4*)(p.conv_w + j * 1536 + col); w[j][1] = *(const f32x4*)(p.conv_w + j * 1536 + col + 4); }
;         u32x4 xr[8];
; #pragma unroll
;         for (int r = 0; r < 8; ++r) { const int mm = m0 + r - 2; xr[r] = (mm >= s0 && mm < s1) ? *(const u32x4*)(PRE + (size_t)mm * 1536 + col) : (u32x4){0u, 0u, 0u, 0u}; }
; __global__ void __launch_bounds__(NTHREADS) mega_fwd(P p) {
;     ...
;                 if (ngw == 2048) {
;                     const int vcu = ((int)blockIdx.x % 8) * (G / 8) + (int)blockIdx.x / 8, gwv = vcu * 8 + wave;
;                     if (RUN(6)) REP(6) {
;                         if (gwv >= 1024) { for (int k = 0; k < 4; ++k) dn_conv_token4(q, ((gwv - 1024) * 4 + k) * 4, lane); }
;                         else if (gwv < 512) dn_conv_token4(q, (4096 + gwv) * 4, lane);
;                     }
;                 } else if (RUN(6)) REP(6) for (int m = gw * 4; m < MALL; m += ngw * 4) dn_conv_token4(q, m, lane);
.LBB0_418:
	s_cmp_eq_u32 s32, 2
	s_cbranch_scc1 .Lst_bar
	v_mov_b32_e32 v0, v1
	s_nop 0
	v_readfirstlane_b32 s2, v0
	s_load_dwordx4 s[72:75], s[92:93], s2 offset:0x60
	s_load_dwordx2 s[8:9], s[92:93], s2 offset:0x70
	s_nop 0
	s_load_dwordx2 s[2:3], s[92:93], s2 offset:0xa8
	v_readfirstlane_b32 s6, v144
	s_ashr_i32 s62, s6, 6
	v_readlane_b32 s6, v253, 58
	v_readlane_b32 s7, v253, 59
	v_and_b32_e32 v110, 63, v144
	s_andn2_b64 vcc, exec, s[6:7]
	s_mov_b64 s[6:7], -1
	s_cbranch_vccnz .LBB0_453
	s_waitcnt lgkmcnt(0)
	v_writelane_b32 v255, s8, 8
	v_readlane_b32 s6, v254, 26
	s_nop 0
	v_writelane_b32 v255, s9, 9
	v_writelane_b32 v255, s72, 10
	s_lshl_b32 s8, s62, 2
	s_add_i32 s16, s8, s6
	v_writelane_b32 v255, s73, 11
	v_writelane_b32 v255, s74, 12
	v_writelane_b32 v255, s75, 13
	s_cmpk_gt_i32 s16, 0x47ff
	s_cbranch_scc1 .LBB0_452
	s_add_u32 s18, s2, 0xfd00000
	v_and_b32_e32 v76, 15, v144
	s_addc_u32 s19, s3, 0
	v_readlane_b32 s10, v255, 8
	v_readlane_b32 s12, v255, 10
	v_lshlrev_b32_e32 v2, 2, v76
	v_mov_b32_e32 v3, v1
	v_readlane_b32 s11, v255, 9
	v_readlane_b32 s14, v255, 12
	v_readlane_b32 s15, v255, 13
	s_add_u32 s22, s2, 0xff00000
	v_lshl_add_u64 v[78:79], s[10:11], 0, v[2:3]
	v_readlane_b32 s13, v255, 11
	v_lshl_add_u64 v[80:81], s[14:15], 0, v[2:3]
	s_addc_u32 s23, s3, 0
	v_lshlrev_b32_e32 v2, 5, v110
	v_lshl_add_u64 v[82:83], s[12:13], 0, v[2:3]
	s_add_u32 s13, s2, 0xb500000
	v_readlane_b32 s9, v254, 23
	s_addc_u32 s14, s3, 0
	s_add_i32 s15, s9, s8
	v_readlane_b32 s9, v254, 24
	s_add_i32 s20, s9, s8
	s_mul_i32 s10, s16, 0xc00
	s_mul_hi_i32 s9, s16, 0xc00
	s_add_u32 s24, s2, s10
	s_addc_u32 s25, s3, s9
	v_readlane_b32 s9, v254, 25
	v_lshlrev_b32_e32 v0, 4, v110
	s_add_i32 s21, s9, s8
	v_readlane_b32 s9, v254, 27
	v_lshl_add_u64 v[74:75], s[2:3], 0, v[0:1]
	v_lshrrev_b32_e32 v77, 4, v110
	v_cmp_lt_u32_e64 s[6:7], 7, v76
	s_add_i32 s12, s9, s8
	s_branch .LBB0_422

; __device__ __forceinline__ unsigned pk2(float lo, float hi) { unsigned r; asm("v_cvt_pk_bf16_f32 %0, %1, %2" : "=v"(r) : "v"(lo), "v"(hi)); return r; }
; __device__ __forceinline__ float siluf(float v) { return v * __builtin_amdgcn_rcpf(1.f + __expf(-v)); }
; __device__ __forceinline__ void dn_conv_token4(const P& p, int m0, int lane) {
;     const bf16_t* PRE = (const bf16_t*)(p.ws + WS_DNPRE);
;     int s0, s1;
;     if (m0 < MLAT) { s0 = m0 & ~2047; s1 = s0 + 2048; } else { s0 = MLAT + ((m0 - MLAT) & ~255); s1 = s0 + 256; }
; #pragma unroll 1
;     for (int cgp = 0; cgp < 3; ++cgp) {
;         const int col = cgp * 512 + lane * 8;
;         f32x4 w[5][2];
; #pragma unroll
;         for (int j = 0; j < 5; ++j) { w[j][0] = *(const f32x4*)(p.conv_w + j * 1536 + col); w[j][1] = *(const f32x4*)(p.conv_w + j * 1536 + col + 4); }
;         u32x4 xr[8];
; #pragma unroll
;         for (int r = 0; r < 8; ++r) { const int mm = m0 + r - 2; xr[r] = (mm >= s0 && mm < s1) ? *(const u32x4*)(PRE + (size_t)mm * 1536 + col) : (u32x4){0u, 0u, 0u, 0u}; }
;         bf16_t* dbase = (bf16_t*)(p.ws + (cgp == 0 ? WS_QN : (cgp == 1 ? WS_KN : WS_VV))) + lane * 8;
; #pragma unroll
;         for (int t = 0; t < 4; ++t) {
;             float acc[8];
; #pragma unroll
;             for (int i = 0; i < 8; ++i) acc[i] = 0.f;
; #pragma unroll
;             for (int j = 0; j < 5; ++j) { const u32x4 xv = xr[t + j];
;                 acc[0] += bflo(xv.x) * w[j][0][0]; acc[1] += bfhi(xv.x) * w[j][0][1]; acc[2] += bflo(xv.y) * w[j][0][2]; acc[3] += bfhi(xv.y) * w[j][0][3];
;                 acc[4] += bflo(xv.z) * w[j][1][0]; acc[5] += bfhi(xv.z) * w[j][1][1]; acc[6] += bflo(xv.w) * w[j][1][2]; acc[7] += bfhi(xv.w) * w[j][1][3]; }
;             float ss = 0.f;
; #pragma unroll
;             for (int i = 0; i < 8; ++i) { acc[i] = siluf(acc[i]); ss += acc[i] * acc[i]; }
;             if (cgp < 2) {
;                 ss += __shfl_xor(ss, 1); ss += __shfl_xor(ss, 2); ss += __shfl_xor(ss, 4); ss += __shfl_xor(ss, 8);
;                 const float rn = 1.0f / sqrtf(ss + EPS);
; #pragma unroll
;                 for (int i = 0; i < 8; ++i) acc[i] *= rn;
;             }
;             u32x4 o; o.x = pk2(acc[0], acc[1]); o.y = pk2(acc[2], acc[3]); o.z = pk2(acc[4], acc[5]); o.w = pk2(acc[6], acc[7]);
;             *(u32x4*)(dbase + (size_t)(m0 + t) * 512) = o;
;         }
.LBB0_422:
	s_mul_i32 s9, s15, 0xc00
	s_mul_hi_i32 s8, s15, 0xc00
	s_add_u32 s26, s13, s9
	s_addc_u32 s27, s14, s8
	s_mul_i32 s9, s20, 0xc00
	s_mul_hi_i32 s8, s20, 0xc00
	s_add_u32 s28, s13, s9
	s_addc_u32 s29, s14, s8
	s_mul_i32 s9, s21, 0xc00
	s_mul_hi_i32 s8, s21, 0xc00
	s_add_u32 s30, s13, s9
	s_addc_u32 s31, s14, s8
	s_mul_i32 s9, s12, 0xc00
	s_mul_hi_i32 s8, s12, 0xc00
	s_add_u32 s34, s13, s9
	s_addc_u32 s35, s14, s8
	s_and_b32 s8, s16, 0xfffff800
	s_and_b32 s10, s16, 0x7fffff00
	s_add_i32 s9, s8, 0x800
	s_add_i32 s11, s10, 0x100
	s_cmpk_lt_i32 s16, 0x4000
	s_cselect_b32 s50, s9, s11
	s_cselect_b32 s52, s8, s10
	s_add_i32 s10, s16, -2
	s_cmp_ge_i32 s10, s52
	s_cselect_b64 s[8:9], -1, 0
	s_cmp_lt_i32 s10, s50
	s_cselect_b64 s[10:11], -1, 0
	s_and_b64 s[40:41], s[8:9], s[10:11]
	s_add_i32 s10, s16, -1
	s_cmp_ge_i32 s10, s52
	s_cselect_b64 s[8:9], -1, 0
	s_cmp_lt_i32 s10, s50
	s_cselect_b64 s[10:11], -1, 0
	s_and_b64 s[42:43], s[8:9], s[10:11]
	s_cmp_ge_i32 s16, s52
	s_cselect_b64 s[8:9], -1, 0
	s_cmp_lt_i32 s16, s50
	s_cselect_b64 s[10:11], -1, 0
	s_and_b64 s[44:45], s[8:9], s[10:11]
	s_ashr_i32 s17, s16, 31
	s_or_b32 s8, s16, 1
	s_cmp_ge_i32 s8, s52
	s_cselect_b64 s[10:11], -1, 0
	s_cmp_lt_i32 s8, s50
	s_cselect_b64 s[46:47], -1, 0
	s_and_b64 s[46:47], s[10:11], s[46:47]
	s_ashr_i32 s9, s8, 31
	s_or_b32 s10, s16, 2
	s_cmp_ge_i32 s10, s52
	s_cselect_b64 s[48:49], -1, 0
	s_cmp_lt_i32 s10, s50
	s_cselect_b64 s[72:73], -1, 0
	s_and_b64 s[48:49], s[48:49], s[72:73]
	s_ashr_i32 s11, s10, 31
	s_or_b32 s72, s16, 3
	s_cmp_ge_i32 s72, s52
	s_cselect_b64 s[74:75], -1, 0
	s_cmp_lt_i32 s72, s50
	s_cselect_b64 s[76:77], -1, 0
	s_and_b64 s[76:77], s[74:75], s[76:77]
	s_ashr_i32 s73, s72, 31
	s_add_i32 s54, s16, 4
	s_cmp_ge_i32 s54, s52
	s_cselect_b64 s[74:75], -1, 0
	s_cmp_lt_i32 s54, s50
	s_cselect_b64 s[78:79], -1, 0
	s_and_b64 s[80:81], s[74:75], s[78:79]
	s_add_i32 s54, s16, 5
	s_cmp_ge_i32 s54, s52
	s_cselect_b64 s[74:75], -1, 0
	s_cmp_lt_i32 s54, s50
	s_cselect_b64 s[78:79], -1, 0
	s_and_b64 s[82:83], s[74:75], s[78:79]
	s_lshl_b64 s[84:85], s[16:17], 10
	s_lshl_b64 s[86:87], s[8:9], 10
	s_lshl_b64 s[88:89], s[10:11], 10
	s_lshl_b64 s[90:91], s[72:73], 10
	s_mov_b64 s[92:93], 0
	s_mov_b64 s[94:95], s[24:25]
	s_branch .LBB0_424
	s_nop 0
	s_nop 0
	s_nop 0
	s_nop 0
	s_nop 0
	s_nop 0
.LBB0_423:
	s_add_u32 s92, s92, 0x800
	s_addc_u32 s93, s93, 0
	s_add_u32 s26, s26, 0x400
	s_addc_u32 s27, s27, 0
	s_add_u32 s28, s28, 0x400
	s_addc_u32 s29, s29, 0
	s_add_u32 s94, s94, 0x400
	s_addc_u32 s95, s95, 0
	s_add_u32 s30, s30, 0x400
	s_addc_u32 s31, s31, 0
	s_add_u32 s34, s34, 0x400
	s_addc_u32 s35, s35, 0
	v_cvt_pk_bf16_f32 v8, v8, v9
	v_cvt_pk_bf16_f32 v9, v2, v3
	v_lshl_add_u64 v[2:3], v[54:55], 0, s[90:91]
	s_cmpk_eq_i32 s92, 0x1800
	v_cvt_pk_bf16_f32 v10, v4, v5
	v_cvt_pk_bf16_f32 v11, v6, v7
	global_store_dwordx4 v[2:3], v[8:11], off
	s_cbranch_scc1 .LBB0_448

; #define REP(k) for (int rep_ = 0; rep_ < (((REPMASK) >> (k)) & 1) + 1; ++rep_)
; __global__ void __launch_bounds__(NTHREADS) mega_fwd(P p) {
;     ...
;                 PH();
;                 {
;                     const int vcu = (G % 8 == 0) ? ((int)blockIdx.x % 8) * (G / 8) + (int)blockIdx.x / 8 : (int)blockIdx.x;
;                     if (RUN(5)) REP(5) for (int t = vcu * 8 + wave; t < 3072; t += ngw) na_task(q, t, lane, (float*)(lds + wave * 12288));
;                 }
;                 PH();
;                 if (ngw == 2048) {
;                     const int vcu = ((int)blockIdx.x % 8) * (G / 8) + (int)blockIdx.x / 8, gwv = vcu * 8 + wave;
;                     if (RUN(6)) REP(6) {
;                         if (gwv >= 1024) { for (int k = 0; k < 4; ++k) dn_conv_token4(q, ((gwv - 1024) * 4 + k) * 4, lane); }
;                         else if (gwv < 512) dn_conv_token4(q, (4096 + gwv) * 4, lane);
;                     }
;                 } else if (RUN(6)) REP(6) for (int m = gw * 4; m < MALL; m += ngw * 4) dn_conv_token4(q, m, lane);
.LBB0_521:
	s_cmp_eq_u32 s32, 1
	s_cbranch_scc0 .Lst_bar
	s_mov_b32 s32, 2
	v_readlane_b32 s92, v254, 54
	v_readlane_b32 s93, v254, 55
	v_mov_b32_e32 v0, v1
	s_mov_b64 exec, -1
	s_branch .Lst_na
